# baseline (speedup 1.0000x reference)
; template <class T> __device__ __forceinline__ T* launder(T* q) { auto g = (__attribute__((address_space(1))) T*)q; asm volatile("" : "+s"(g)); return (T*)g; }
; __device__ __forceinline__ float b2f(u16 b) { return __uint_as_float(((unsigned)b) << 16); }
; __device__ __forceinline__ void post_phase(const Params& p, int j, u16* Y, const u16* V, const u16* YB) {
;     ...
;   char* ws_ = launder(p.ws);
;   const u16* gmid = (const u16*)(ws_ + OFF_GMID);
;   const u16* g2T = (const u16*)(ws_ + OFF_G2T);
;   const unsigned* bon = (const unsigned*)(ws_ + OFF_VMID);
;   const float* lg = inp(p, 22) + (size_t)j * CM;
;   const float* lb = inp(p, 23) + (size_t)j * CM;
;   for (int it = blockIdx.x; it < NTOK / 16; it += gridDim.x) {
;     asm volatile("" ::: "memory");
;     int tok = it * 16 + fr;
;     bool sample = (it * 16 >= NPROMPT);
;     bf16x8 gb[5];
;     _Pragma("unroll") for (int ks = 0; ks < 5; ++ks) gb[ks] = ld8(gmid + (size_t)tok * 160 + ks * 32 + fq * 8);
;     _Pragma("unroll") for (int hh = 0; hh < 2; ++hh) {
;       int hd = wv * 2 + hh;
;       bf16x8 ga[4][5]; uint2 yr[4], vr[4], yb2[4];
;       _Pragma("unroll") for (int m = 0; m < 4; ++m) {
;         int ch0 = hd * 64 + m * 16;
;         _Pragma("unroll") for (int ks = 0; ks < 5; ++ks) ga[m][ks] = ld8(g2T + (size_t)(ch0 + fr) * 160 + ks * 32 + fq * 8);
;         yr[m] = *reinterpret_cast<const uint2*>(Y + (size_t)tok * CM + ch0 + fq * 4);
;         vr[m] = *reinterpret_cast<const uint2*>(V + (size_t)tok * CM + ch0 + fq * 4);
;         yb2[m] = sample ? *reinterpret_cast<const uint2*>(YB + (size_t)(tok - NPROMPT) * CM + ch0 + fq * 4) : make_uint2(0u, 0u);
;       }
;       unsigned bw_ = bon[(size_t)tok * 16 + hd];
;       float bonus = b2f((u16)(bw_ & 0xffffu)) + b2f((u16)(bw_ >> 16));
;       float yv[4][4], s1 = 0.f;
;       _Pragma("unroll") for (int m = 0; m < 4; ++m) {
;         yv[m][0] = b2f((u16)(yr[m].x & 0xffffu)) + b2f((u16)(yb2[m].x & 0xffffu)); yv[m][1] = b2f((u16)(yr[m].x >> 16)) + b2f((u16)(yb2[m].x >> 16));
;         yv[m][2] = b2f((u16)(yr[m].y & 0xffffu)) + b2f((u16)(yb2[m].y & 0xffffu)); yv[m][3] = b2f((u16)(yr[m].y >> 16)) + b2f((u16)(yb2[m].y >> 16));
;         s1 += yv[m][0] + yv[m][1] + yv[m][2] + yv[m][3];
;       }
;       s1 += shx(s1, 16, lane); s1 += shx(s1, 32, lane);
;       float mu = s1 * (1.f / 64.f), s2 = 0.f;
.LBB0_2807:
	s_or_b64 exec, exec, s[0:1]
	v_readlane_b32 s68, v248, 2
	v_readlane_b32 s69, v248, 3
	v_readlane_b32 s70, v248, 4
	v_readlane_b32 s71, v248, 5
	v_readlane_b32 s72, v248, 6
	v_readlane_b32 s73, v248, 7
	v_readlane_b32 s74, v248, 8
	v_readlane_b32 s75, v248, 9
	v_readlane_b32 s76, v248, 10
	v_readlane_b32 s77, v248, 11
	v_readlane_b32 s78, v248, 12
	v_readlane_b32 s79, v248, 13
	v_readlane_b32 s80, v248, 14
	v_readlane_b32 s81, v248, 15
	v_readlane_b32 s82, v248, 16
	v_readlane_b32 s83, v248, 17
	s_mov_b64 s[6:7], s[82:83]
	v_readlane_b32 s68, v248, 52
	v_readlane_b32 s80, v247, 0
	v_readlane_b32 s81, v247, 1
	v_readlane_b32 s82, v247, 2
	v_readlane_b32 s83, v247, 3
	v_mov_b32_e32 v0, v131
	s_mov_b64 s[8:9], s[80:81]
	s_mov_b64 s[10:11], s[82:83]
	s_and_b64 vcc, exec, s[14:15]
	v_readlane_b32 s81, v246, 16
	s_barrier
	v_readlane_b32 s69, v248, 53
	v_readlane_b32 s70, v248, 54
	v_readlane_b32 s71, v248, 55
	v_readlane_b32 s72, v248, 56
	v_readlane_b32 s73, v248, 57
	v_readlane_b32 s74, v248, 58
	v_readlane_b32 s75, v248, 59
	v_readlane_b32 s76, v248, 60
	v_readlane_b32 s77, v248, 61
	v_readlane_b32 s78, v248, 62
	v_readlane_b32 s79, v248, 63
	s_cbranch_vccnz .LBB0_2826
	v_readlane_b32 s2, v246, 38
	s_add_u32 s0, s6, 0x34e00000
	v_readlane_b32 s3, v246, 39
	s_addc_u32 s1, s7, 0
	s_lshl_b64 s[2:3], s[2:3], 2
	v_ashrrev_i32_e32 v9, 5, v0
	s_add_u32 s10, s10, s2
	v_lshrrev_b32_e32 v1, 1, v0
	v_and_b32_e32 v2, 48, v0
	v_mov_b32_e32 v3, v129
	v_and_b32_e32 v102, -2, v9
	v_and_b32_e32 v8, 15, v0
	s_addc_u32 s11, s11, s3
	v_and_b32_e32 v128, 24, v1
	s_waitcnt vmcnt(0)
	v_lshl_add_u64 v[4:5], s[6:7], 0, v[2:3]
	s_mov_b64 s[6:7], 0x33000000
	v_lshlrev_b32_e32 v110, 6, v102
	s_add_u32 s2, s8, s2
	v_lshl_add_u64 v[100:101], v[4:5], 0, s[6:7]
	s_mov_b64 s[6:7], 0x3f480000
	v_lshl_add_u64 v[106:107], s[4:5], 0, v[128:129]
	v_lshlrev_b32_e32 v0, 2, v0
	s_movk_i32 s4, 0x80
	v_or_b32_e32 v6, v110, v8
	s_addc_u32 s3, s9, s3
	v_lshl_add_u64 v[4:5], v[4:5], 0, s[6:7]
	v_bitop3_b32 v193, v0, s4, v185 bitop3:0x6c
	s_movk_i32 s4, 0x140
	v_or_b32_e32 v7, 16, v6
	v_lshl_add_u64 v[104:105], s[66:67], 0, v[128:129]
	v_lshl_add_u64 v[108:109], s[94:95], 0, v[128:129]
	v_bitop3_b32 v128, v0, 64, v185 bitop3:0x6c
	v_lshl_add_u64 v[0:1], s[2:3], 0, v[2:3]
	v_mad_i64_i32 v[112:113], s[2:3], v6, s4, v[4:5]
	v_ashrrev_i32_e32 v111, 31, v110
	v_mad_i64_i32 v[114:115], s[2:3], v7, s4, v[4:5]
	v_or_b32_e32 v7, 32, v6
	v_or_b32_e32 v6, 48, v6
	v_or_b32_e32 v124, 1, v9
	v_lshl_add_u64 v[2:3], s[10:11], 0, v[2:3]
	v_mad_i64_i32 v[116:117], s[2:3], v7, s4, v[4:5]
	v_mad_i64_i32 v[118:119], s[2:3], v6, s4, v[4:5]
	v_lshlrev_b64 v[6:7], 2, v[110:111]
	v_lshlrev_b32_e32 v126, 6, v124
	v_lshl_add_u64 v[120:121], v[0:1], 0, v[6:7]
	v_lshl_add_u64 v[122:123], v[2:3], 0, v[6:7]
	v_or_b32_e32 v6, v126, v8
	v_or_b32_e32 v7, 16, v6
	v_mad_i64_i32 v[132:133], s[2:3], v6, s4, v[4:5]
	v_mad_i64_i32 v[134:135], s[2:3], v7, s4, v[4:5]
	v_or_b32_e32 v7, 32, v6
	v_or_b32_e32 v6, 48, v6
	v_ashrrev_i32_e32 v127, 31, v126
	v_mad_i64_i32 v[136:137], s[2:3], v7, s4, v[4:5]
	v_mad_i64_i32 v[138:139], s[2:3], v6, s4, v[4:5]
	v_lshlrev_b64 v[4:5], 2, v[126:127]
	v_readlane_b32 s2, v247, 32
	v_ashrrev_i32_e32 v103, 31, v102
	v_ashrrev_i32_e32 v125, 31, v124
	v_lshl_add_u64 v[140:141], v[0:1], 0, v[4:5]
	v_lshl_add_u64 v[142:143], v[2:3], 0, v[4:5]
	v_add_u32_e32 v144, s2, v8
	v_add_u32_e32 v144, 0x17000, v144
	s_add_i32 s2, s92, 0x1700
	s_branch .LBB0_2810
.LBB0_2809:
	v_lshl_add_u64 v[154:155], v[124:125], 2, v[154:155]
	global_load_dword v145, v[154:155], off
	s_waitcnt vmcnt(27)
	v_mfma_f32_16x16x32_bf16 v[96:99], v[96:99], v[16:19], 0
	s_waitcnt vmcnt(16)
	v_lshlrev_b32_e32 v176, 16, v172
	s_waitcnt vmcnt(15)
	v_lshlrev_b32_e32 v178, 16, v168
	v_and_b32_e32 v177, 0xffff0000, v172
	v_mfma_f32_16x16x32_bf16 v[92:95], v[92:95], v[12:15], v[96:99]
	v_and_b32_e32 v179, 0xffff0000, v168
	v_lshlrev_b32_e32 v154, 16, v166
	v_lshlrev_b32_e32 v174, 16, v170
	v_mfma_f32_16x16x32_bf16 v[88:91], v[88:91], v[8:11], v[92:95]
	v_and_b32_e32 v155, 0xffff0000, v166
	v_and_b32_e32 v175, 0xffff0000, v170
	v_pk_add_f32 v[176:177], v[176:177], v[178:179]
	v_mfma_f32_16x16x32_bf16 v[84:87], v[84:87], v[4:7], v[88:91]
	v_lshlrev_b32_e32 v179, 16, v173
	v_lshlrev_b32_e32 v181, 16, v169
	v_and_b32_e32 v178, 0xffff0000, v173
	v_mfma_f32_16x16x32_bf16 v[80:83], v[80:83], v[0:3], v[84:87]
	s_nop 3
	global_load_dwordx4 v[84:87], v[140:141], off
	global_load_dwordx4 v[88:91], v[142:143], off
	global_load_dwordx4 v[202:205], v[140:141], off offset:64
	global_load_dwordx4 v[206:209], v[142:143], off offset:64
	global_load_dwordx4 v[210:213], v[140:141], off offset:128
	global_load_dwordx4 v[214:217], v[142:143], off offset:128
	global_load_dwordx4 v[218:221], v[140:141], off offset:192
	global_load_dwordx4 v[222:225], v[142:143], off offset:192
	v_and_b32_e32 v180, 0xffff0000, v169
	v_lshlrev_b32_e32 v166, 16, v167
	v_lshlrev_b32_e32 v170, 16, v171
	v_and_b32_e32 v167, 0xffff0000, v167
	v_and_b32_e32 v171, 0xffff0000, v171
	v_pk_add_f32 v[168:169], v[178:179], v[180:181]
	v_pk_add_f32 v[172:173], v[176:177], v[176:177] op_sel:[0,1] op_sel_hi:[1,0]
	v_pk_add_f32 v[154:155], v[154:155], v[174:175]
	v_pk_add_f32 v[172:173], v[172:173], v[168:169] op_sel:[0,1] op_sel_hi:[1,0]
	v_pk_add_f32 v[166:167], v[166:167], v[170:171]
	v_add_f32_e32 v94, v154, v155
	v_pk_add_f32 v[96:97], v[168:169], v[172:173]
	s_waitcnt vmcnt(16)
	v_lshlrev_b32_e32 v98, 16, v162
	v_lshlrev_b32_e32 v172, 16, v158
	v_and_b32_e32 v99, 0xffff0000, v162
	v_and_b32_e32 v173, 0xffff0000, v158
	v_add_f32_e32 v94, v94, v166
	v_add_f32_e32 v94, v167, v94
	v_pk_add_f32 v[98:99], v[172:173], v[98:99]
	v_and_b32_e32 v92, 0xffff0000, v163
	s_waitcnt vmcnt(9)
; __device__ __forceinline__ float b2f(u16 b) { return __uint_as_float(((unsigned)b) << 16); }
; __device__ __forceinline__ void post_phase(const Params& p, int j, u16* Y, const u16* V, const u16* YB) {
;     ...
;   for (int it = blockIdx.x; it < NTOK / 16; it += gridDim.x) {
;     ...
;       float bonus = b2f((u16)(bw_ & 0xffffu)) + b2f((u16)(bw_ >> 16));
;       float yv[4][4], s1 = 0.f;
;       _Pragma("unroll") for (int m = 0; m < 4; ++m) {
;         yv[m][0] = b2f((u16)(yr[m].x & 0xffffu)) + b2f((u16)(yb2[m].x & 0xffffu)); yv[m][1] = b2f((u16)(yr[m].x >> 16)) + b2f((u16)(yb2[m].x >> 16));
;         yv[m][2] = b2f((u16)(yr[m].y & 0xffffu)) + b2f((u16)(yb2[m].y & 0xffffu)); yv[m][3] = b2f((u16)(yr[m].y >> 16)) + b2f((u16)(yb2[m].y >> 16));
;         s1 += yv[m][0] + yv[m][1] + yv[m][2] + yv[m][3];
;       }
;       s1 += shx(s1, 16, lane); s1 += shx(s1, 32, lane);
;       float mu = s1 * (1.f / 64.f), s2 = 0.f;
;       _Pragma("unroll") for (int m = 0; m < 4; ++m) _Pragma("unroll") for (int e = 0; e < 4; ++e) { float dd = yv[m][e] - mu; s2 += dd * dd; }
;       s2 += shx(s2, 16, lane); s2 += shx(s2, 32, lane);
;       float rsd = rsqrtf(s2 * (1.f / 64.f) + 64e-5f);
	v_and_b32_e32 v95, 0xffff0000, v160
	v_lshlrev_b32_e32 v93, 16, v161
	v_and_b32_e32 v97, 0xffff0000, v161
	v_add_f32_e32 v158, 0, v94
	v_lshlrev_b32_e32 v171, 16, v164
	v_lshlrev_b32_e32 v170, 16, v159
	v_lshlrev_b32_e32 v161, 16, v160
	v_lshlrev_b32_e32 v160, 16, v163
	v_and_b32_e32 v163, 0xffff0000, v164
	v_mov_b32_e32 v162, v98
	v_mov_b32_e32 v94, v99
	v_pk_add_f32 v[160:161], v[170:171], v[160:161]
	v_and_b32_e32 v170, 0xffff0000, v159
	v_lshlrev_b32_e32 v171, 16, v165
	v_and_b32_e32 v159, 0xffff0000, v165
	v_pk_add_f32 v[94:95], v[162:163], v[94:95]
	v_pk_add_f32 v[92:93], v[170:171], v[92:93]
	v_pk_add_f32 v[96:97], v[158:159], v[96:97]
	v_pk_add_f32 v[158:159], v[160:161], v[94:95]
	v_mfma_f32_16x16x32_bf16 v[76:79], v[76:79], v[16:19], 0
	v_add_f32_e64 v158, v158, v92
	v_add_f32_e64 v159, v159, v93
	s_sub_i32 s2, s2, s81
	v_pk_add_f32 v[158:159], v[96:97], v[158:159]
	v_mfma_f32_16x16x32_bf16 v[72:75], v[72:75], v[12:15], v[76:79]
	v_add_f32_e32 v94, v158, v159
	ds_bpermute_b32 v158, v128, v94
	v_mov_b32_e32 v96, v97
	v_mfma_f32_16x16x32_bf16 v[68:71], v[68:71], v[8:11], v[72:75]
	v_mov_b32_e32 v97, v93
	s_cmp_gt_i32 s2, -1
	s_waitcnt lgkmcnt(0)
	v_add_f32_e32 v76, v94, v158
	ds_bpermute_b32 v77, v193, v76
	v_mov_b32_e32 v73, v92
	v_mov_b32_e32 v72, v160
	v_mov_b32_e32 v160, v95
	v_mfma_f32_16x16x32_bf16 v[64:67], v[64:67], v[16:19], 0
	s_waitcnt lgkmcnt(0)
	v_add_f32_e32 v74, v76, v77
	v_mul_f32_e32 v74, 0x3c800000, v74
	v_pk_add_f32 v[76:77], v[154:155], v[74:75] op_sel_hi:[1,0] neg_lo:[0,1] neg_hi:[0,1]
	v_pk_add_f32 v[92:93], v[166:167], v[74:75] op_sel_hi:[1,0] neg_lo:[0,1] neg_hi:[0,1]
	v_pk_mul_f32 v[78:79], v[76:77], v[76:77]
	v_pk_mul_f32 v[154:155], v[92:93], v[92:93]
	v_add_f32_e32 v78, v78, v79
	v_pk_add_f32 v[164:165], v[168:169], v[74:75] op_sel_hi:[1,0] neg_lo:[0,1] neg_hi:[0,1]
	v_pk_add_f32 v[168:169], v[176:177], v[74:75] op_sel_hi:[1,0] neg_lo:[0,1] neg_hi:[0,1]
	v_add_f32_e32 v78, v154, v78
	v_pk_mul_f32 v[170:171], v[168:169], v[168:169]
	v_add_f32_e32 v78, v155, v78
	v_add_f32_e32 v78, v170, v78
	v_pk_mul_f32 v[166:167], v[164:165], v[164:165]
	v_add_f32_e32 v78, v171, v78
	v_pk_add_f32 v[98:99], v[98:99], v[74:75] op_sel_hi:[1,0] neg_lo:[0,1] neg_hi:[0,1]
	v_add_f32_e32 v78, v167, v78
	v_pk_mul_f32 v[158:159], v[98:99], v[98:99]
	v_add_f32_e32 v78, v166, v78
	v_pk_add_f32 v[72:73], v[72:73], v[74:75] op_sel_hi:[1,0] neg_lo:[0,1] neg_hi:[0,1]
	v_add_f32_e32 v78, v158, v78
	v_pk_add_f32 v[94:95], v[160:161], v[74:75] op_sel_hi:[1,0] neg_lo:[0,1] neg_hi:[0,1]
	v_pk_add_f32 v[96:97], v[96:97], v[74:75] op_sel_hi:[1,0] neg_lo:[0,1] neg_hi:[0,1]
	v_pk_mul_f32 v[74:75], v[72:73], v[72:73]
	v_add_f32_e32 v78, v159, v78
	v_add_f32_e32 v74, v74, v78
	v_pk_mul_f32 v[160:161], v[94:95], v[94:95]
	v_add_f32_e32 v74, v75, v74
	v_add_f32_e32 v74, v161, v74
	v_pk_mul_f32 v[162:163], v[96:97], v[96:97]
	v_add_f32_e32 v74, v160, v74
	v_add_f32_e32 v74, v163, v74
	v_add_f32_e32 v74, v162, v74
	ds_bpermute_b32 v75, v128, v74
	s_waitcnt vmcnt(8)
	v_lshlrev_b32_e32 v78, 16, v145
	v_and_b32_e32 v79, 0xffff0000, v145
	v_mfma_f32_16x16x32_bf16 v[60:63], v[60:63], v[12:15], v[64:67]
	s_waitcnt lgkmcnt(0)
	v_add_f32_e32 v75, v74, v75
	ds_bpermute_b32 v145, v193, v75
	v_mfma_f32_16x16x32_bf16 v[56:59], v[56:59], v[8:11], v[60:63]
	v_add_f32_e32 v74, v78, v79
	v_lshlrev_b32_e32 v78, 16, v156
	v_and_b32_e32 v79, 0xffff0000, v156
	s_waitcnt lgkmcnt(0)
; __device__ __forceinline__ unsigned pk2(float a, float b) { f2_t x; x[0] = a; x[1] = b; return __builtin_bit_cast(unsigned, __builtin_convertvector(x, bf2_t)); }
; __device__ __forceinline__ float b2f(u16 b) { return __uint_as_float(((unsigned)b) << 16); }
; #define MFMA16(a, b, c) __builtin_amdgcn_mfma_f32_16x16x32_bf16(a, b, c, 0, 0, 0)
; __device__ __forceinline__ void post_phase(const Params& p, int j, u16* Y, const u16* V, const u16* YB) {
;     ...
;       float rsd = rsqrtf(s2 * (1.f / 64.f) + 64e-5f);
;       _Pragma("unroll") for (int m = 0; m < 4; ++m) {
;         int ch0 = hd * 64 + m * 16;
;         f32x4 g = {0.f, 0.f, 0.f, 0.f};
;         _Pragma("unroll") for (int ks = 0; ks < 5; ++ks) g = MFMA16(ga[m][ks], gb[ks], g);
;         float4 lg4 = *reinterpret_cast<const float4*>(lg + ch0 + fq * 4);
;         float4 lb4 = *reinterpret_cast<const float4*>(lb + ch0 + fq * 4);
;         float vv0 = b2f((u16)(vr[m].x & 0xffffu)), vv1 = b2f((u16)(vr[m].x >> 16));
;         float vv2 = b2f((u16)(vr[m].y & 0xffffu)), vv3 = b2f((u16)(vr[m].y >> 16));
;         float o0 = ((yv[m][0] - mu) * rsd * lg4.x + lb4.x + bonus * vv0) * g[0];
;         float o1 = ((yv[m][1] - mu) * rsd * lg4.y + lb4.y + bonus * vv1) * g[1];
;         float o2 = ((yv[m][2] - mu) * rsd * lg4.z + lb4.z + bonus * vv2) * g[2];
;         float o3 = ((yv[m][3] - mu) * rsd * lg4.w + lb4.w + bonus * vv3) * g[3];
;         uint2 o; o.x = pk2(o0, o1); o.y = pk2(o2, o3);
;         *reinterpret_cast<uint2*>(Y + (size_t)tok * CM + ch0 + fq * 4) = o;
	v_add_f32_e32 v64, v75, v145
	v_fmamk_f32 v64, v64, 0x3c800000, v184
	v_mul_f32_e32 v65, 0x4b800000, v64
	v_cmp_gt_f32_e32 vcc, s3, v64
	v_mfma_f32_16x16x32_bf16 v[16:19], v[52:55], v[16:19], 0
	v_readlane_b32 s3, v246, 17
	v_cndmask_b32_e32 v64, v64, v65, vcc
	v_rsq_f32_e32 v66, v64
	v_lshlrev_b32_e32 v64, 16, v157
	v_and_b32_e32 v65, 0xffff0000, v157
	v_mfma_f32_16x16x32_bf16 v[12:15], v[48:51], v[12:15], v[16:19]
	v_mul_f32_e32 v60, 0x45800000, v66
	v_cndmask_b32_e32 v60, v66, v60, vcc
	v_pk_mul_f32 v[62:63], v[76:77], v[60:61] op_sel_hi:[1,0]
	v_pk_mul_f32 v[66:67], v[92:93], v[60:61] op_sel_hi:[1,0]
	s_waitcnt vmcnt(6)
	v_pk_fma_f32 v[62:63], v[84:85], v[62:63], v[88:89]
	v_pk_fma_f32 v[66:67], v[86:87], v[66:67], v[90:91]
	v_pk_fma_f32 v[62:63], v[74:75], v[78:79], v[62:63] op_sel_hi:[0,1,1]
	v_pk_fma_f32 v[64:65], v[74:75], v[64:65], v[66:67] op_sel_hi:[0,1,1]
	v_pk_mul_f32 v[62:63], v[80:81], v[62:63]
	v_pk_mul_f32 v[64:65], v[82:83], v[64:65]
	v_cvt_pk_bf16_f32 v62, v62, v63
	v_cvt_pk_bf16_f32 v63, v64, v65
	global_store_dwordx2 v[146:147], v[62:63], off
	s_nop 0
	s_nop 0
	v_mfma_f32_16x16x32_bf16 v[40:43], v[40:43], v[4:7], v[68:71]
	v_lshlrev_b32_e32 v48, 16, v150
	v_and_b32_e32 v49, 0xffff0000, v150
	v_lshlrev_b32_e32 v50, 16, v151
	v_mfma_f32_16x16x32_bf16 v[32:35], v[32:35], v[0:3], v[40:43]
	v_and_b32_e32 v51, 0xffff0000, v151
	v_subrev_u32_e32 v144, s3, v144
	s_nop 1
	v_pk_mul_f32 v[40:41], v[168:169], v[60:61] op_sel_hi:[1,0]
	v_pk_mul_f32 v[42:43], v[164:165], v[60:61] op_sel_hi:[1,0]
	v_mfma_f32_16x16x32_bf16 v[8:11], v[28:31], v[8:11], v[12:15]
	s_waitcnt vmcnt(5)
	v_pk_fma_f32 v[16:17], v[202:203], v[40:41], v[206:207]
	v_pk_fma_f32 v[18:19], v[204:205], v[42:43], v[208:209] op_sel:[0,1,0] op_sel_hi:[1,0,1]
	v_pk_fma_f32 v[16:17], v[74:75], v[48:49], v[16:17] op_sel_hi:[0,1,1]
	v_pk_fma_f32 v[18:19], v[74:75], v[50:51], v[18:19] op_sel_hi:[0,1,1]
	v_pk_mul_f32 v[16:17], v[32:33], v[16:17]
	v_pk_mul_f32 v[18:19], v[34:35], v[18:19]
	v_cvt_pk_bf16_f32 v16, v16, v17
	v_cvt_pk_bf16_f32 v17, v18, v19
	global_store_dwordx2 v[146:147], v[16:17], off offset:32
	s_nop 0
	s_nop 0
	s_nop 0
	v_mfma_f32_16x16x32_bf16 v[40:43], v[44:47], v[4:7], v[56:59]
	v_lshlrev_b32_e32 v48, 16, v152
	v_and_b32_e32 v49, 0xffff0000, v152
	v_lshlrev_b32_e32 v44, 16, v153
	v_mfma_f32_16x16x32_bf16 v[36:39], v[36:39], v[0:3], v[40:43]
	v_and_b32_e32 v45, 0xffff0000, v153
	v_lshlrev_b32_e32 v12, 16, v148
	v_and_b32_e32 v13, 0xffff0000, v148
	s_nop 0
	v_pk_mul_f32 v[40:41], v[98:99], v[60:61] op_sel_hi:[1,0]
	v_pk_mul_f32 v[42:43], v[72:73], v[60:61] op_sel_hi:[1,0]
	v_mfma_f32_16x16x32_bf16 v[4:7], v[24:27], v[4:7], v[8:11]
	v_lshlrev_b32_e32 v14, 16, v149
	v_and_b32_e32 v15, 0xffff0000, v149
	s_waitcnt vmcnt(4)
	v_pk_fma_f32 v[16:17], v[40:41], v[210:211], v[214:215]
	v_pk_fma_f32 v[18:19], v[42:43], v[212:213], v[216:217]
	v_pk_fma_f32 v[16:17], v[74:75], v[48:49], v[16:17] op_sel_hi:[0,1,1]
	v_pk_fma_f32 v[18:19], v[74:75], v[44:45], v[18:19] op_sel_hi:[0,1,1]
	v_pk_mul_f32 v[16:17], v[36:37], v[16:17]
	v_pk_mul_f32 v[18:19], v[38:39], v[18:19]
	v_cvt_pk_bf16_f32 v16, v16, v17
	v_cvt_pk_bf16_f32 v17, v18, v19
	global_store_dwordx2 v[146:147], v[16:17], off offset:64
	s_nop 0
	s_nop 0
	s_nop 0
	v_mfma_f32_16x16x32_bf16 v[0:3], v[20:23], v[0:3], v[4:7]
	s_nop 2
	v_mul_f32_e64 v4, v94, v60
	v_mul_f32_e64 v5, v95, v60
	v_pk_mul_f32 v[6:7], v[96:97], v[60:61] op_sel_hi:[1,0]
	s_waitcnt vmcnt(3)
	v_pk_fma_f32 v[4:5], v[4:5], v[218:219], v[222:223] op_sel:[1,0,0] op_sel_hi:[0,1,1]
	v_pk_fma_f32 v[6:7], v[6:7], v[220:221], v[224:225] op_sel:[1,0,0] op_sel_hi:[0,1,1]
	v_pk_fma_f32 v[4:5], v[74:75], v[12:13], v[4:5] op_sel_hi:[0,1,1]
	v_pk_fma_f32 v[6:7], v[74:75], v[14:15], v[6:7] op_sel_hi:[0,1,1]
	v_pk_mul_f32 v[0:1], v[0:1], v[4:5]
	v_pk_mul_f32 v[2:3], v[2:3], v[6:7]
	v_cvt_pk_bf16_f32 v0, v0, v1
	v_cvt_pk_bf16_f32 v1, v2, v3
	global_store_dwordx2 v[146:147], v[0:1], off offset:96
	s_cbranch_scc0 .LBB0_2826
